# attention: s_setprio 1 for waves 4-7 from S1 start until after PV MFMA 4, on top of hand-scheduled S2
# baseline (speedup 1.0000x reference)
; #define LOADV(dst, ks_) do { _Pragma("unroll") for (int dvb = 0; dvb < 4; ++dvb) { dst[2 * dvb] = vtr(vp + dvb * 4096 + (ks_) * 1024); dst[2 * dvb + 1] = vtr(vp + dvb * 4096 + (ks_) * 1024 + 512); } } while (0)
; #define MF4(src, pfrag) do { _Pragma("unroll") for (int dvb = 0; dvb < 4; ++dvb) { \
;         const bf16x8 vf_ = __builtin_shufflevector(src[2 * dvb], src[2 * dvb + 1], 0, 1, 2, 3, 4, 5, 6, 7); o[dvb] = MFMA32(vf_, pfrag, o[dvb]); } } while (0)
; #define EXPQ(S, lo_, RS, PF) do { _Pragma("unroll") for (int i = lo_; i < lo_ + 8; ++i) { S[i] = ex2(S[i]); RS += S[i]; } \
;               u32x4 w_; w_.x = pk2(S[lo_], S[lo_ + 1]); w_.y = pk2(S[lo_ + 2], S[lo_ + 3]); w_.z = pk2(S[lo_ + 4], S[lo_ + 5]); w_.w = pk2(S[lo_ + 6], S[lo_ + 7]); PF = __builtin_bit_cast(bf16x8, w_); } while (0)
; DI void attn_unit(const Params& p, int bh, int qb, char* lds, float lam, int tid, int lane, int wid, const bool build_tab) {
;     ...
;             float rs0 = 0.f, rs1 = 0.f;
;     ...
;             EXPQ(s0, 0, rs0, pf[0]);
;             LOADV(vb, 1);
;             MF4(va, pf[0]);
;             EXPQ(s0, 8, rs1, pf[1]);
;             LOADV(va, 2);
;             MF4(vb, pf[1]);
;             EXPQ(s1, 0, rs0, pf[2]);
;             LOADV(vb, 3);
;             MF4(va, pf[2]);
;             EXPQ(s1, 8, rs1, pf[3]);
;             MF4(vb, pf[3]);
;             l += rs0 + rs1;
.LBB0_359:
	ds_read_b64_tr_b16 v[242:243], v220 offset:21504
	ds_read_b64_tr_b16 v[244:245], v220 offset:22016
	ds_read_b64_tr_b16 v[246:247], v220 offset:25600
	ds_read_b64_tr_b16 v[248:249], v220 offset:26112
	v_exp_f32_e32 v222, v96
	v_exp_f32_e32 v224, v97
	v_exp_f32_e32 v226, v98
	v_exp_f32_e32 v228, v99
	v_exp_f32_e32 v230, v100
	v_exp_f32_e32 v232, v101
	v_exp_f32_e32 v234, v102
	v_exp_f32_e32 v236, v103
	v_cvt_pk_bf16_f32 v96, v222, v224
	v_cvt_pk_bf16_f32 v97, v226, v228
	v_cvt_pk_bf16_f32 v98, v230, v232
	v_cvt_pk_bf16_f32 v99, v234, v236
	ds_read_b64_tr_b16 v[100:101], v220 offset:17408
	ds_read_b64_tr_b16 v[102:103], v220 offset:17920
	s_waitcnt lgkmcnt(12)
	v_mfma_f32_32x32x16_bf16 v[48:63], v[140:143], v[96:99], v[48:63]
	ds_read_b64_tr_b16 v[250:251], v220 offset:29696
	ds_read_b64_tr_b16 v[252:253], v220 offset:30208
	v_exp_f32_e32 v223, v104
	v_exp_f32_e32 v225, v105
	v_exp_f32_e32 v227, v106
	v_add_f32_e32 v221, v224, v222
	s_waitcnt lgkmcnt(12)
	v_mfma_f32_32x32x16_bf16 v[32:47], v[136:139], v[96:99], v[32:47]
	v_exp_f32_e32 v229, v107
	v_exp_f32_e32 v231, v108
	v_exp_f32_e32 v233, v109
	v_add_f32_e32 v221, v226, v221
	s_waitcnt lgkmcnt(10)
	v_mfma_f32_32x32x16_bf16 v[16:31], v[132:135], v[96:99], v[16:31]
	v_exp_f32_e32 v235, v110
	v_exp_f32_e32 v237, v111
	v_add_f32_e32 v221, v228, v221
	v_add_f32_e32 v221, v230, v221
	ds_read_b64_tr_b16 v[104:105], v220 offset:18432
	ds_read_b64_tr_b16 v[106:107], v220 offset:18944
	ds_read_b64_tr_b16 v[108:109], v220 offset:19456
	ds_read_b64_tr_b16 v[110:111], v220 offset:19968
	s_waitcnt lgkmcnt(12)
	v_mfma_f32_32x32x16_bf16 v[0:15], v[128:131], v[96:99], v[0:15]
	s_setprio 0
	ds_read_b64_tr_b16 v[128:129], v220 offset:26624
	ds_read_b64_tr_b16 v[130:131], v220 offset:27136
	v_cvt_pk_bf16_f32 v96, v223, v225
	v_cvt_pk_bf16_f32 v97, v227, v229
	v_cvt_pk_bf16_f32 v98, v231, v233
	v_cvt_pk_bf16_f32 v99, v235, v237
	v_exp_f32_e32 v140, v84
	v_exp_f32_e32 v142, v85
	s_waitcnt lgkmcnt(8)
	v_mfma_f32_32x32x16_bf16 v[48:63], v[100:103], v[96:99], v[48:63]
	v_exp_f32_e32 v238, v86
	v_exp_f32_e32 v240, v87
	v_add_f32_e32 v221, v232, v221
	ds_read_b64_tr_b16 v[84:85], v220 offset:22528
	ds_read_b64_tr_b16 v[86:87], v220 offset:23040
	v_exp_f32_e32 v136, v82
	s_waitcnt lgkmcnt(14)
	v_mfma_f32_32x32x16_bf16 v[32:47], v[242:245], v[96:99], v[32:47]
	ds_read_b64_tr_b16 v[242:243], v220 offset:23552
	ds_read_b64_tr_b16 v[244:245], v220 offset:24064
	v_exp_f32_e32 v138, v83
	v_exp_f32_e32 v132, v80
	v_exp_f32_e32 v134, v81
	v_add_f32_e32 v221, v234, v221
	s_waitcnt lgkmcnt(14)
	v_mfma_f32_32x32x16_bf16 v[16:31], v[246:249], v[96:99], v[16:31]
	ds_read_b64_tr_b16 v[246:247], v220 offset:27648
	ds_read_b64_tr_b16 v[248:249], v220 offset:28160
	v_cvt_pk_bf16_f32 v80, v132, v134
	v_cvt_pk_bf16_f32 v81, v136, v138
	v_cvt_pk_bf16_f32 v82, v140, v142
	v_cvt_pk_bf16_f32 v83, v238, v240
	v_exp_f32_e32 v133, v88
	v_exp_f32_e32 v135, v89
	s_waitcnt lgkmcnt(12)
	v_mfma_f32_32x32x16_bf16 v[0:15], v[250:253], v[96:99], v[0:15]
	ds_read_b64_tr_b16 v[250:251], v220 offset:31744
	ds_read_b64_tr_b16 v[252:253], v220 offset:32256
	v_exp_f32_e32 v137, v90
	v_exp_f32_e32 v139, v91
	v_add_f32_e32 v221, v236, v221
	ds_read_b64_tr_b16 v[88:89], v220 offset:30720
	ds_read_b64_tr_b16 v[90:91], v220 offset:31232
	v_exp_f32_e32 v141, v92
	s_waitcnt lgkmcnt(14)
	v_mfma_f32_32x32x16_bf16 v[48:63], v[104:107], v[80:83], v[48:63]
	v_exp_f32_e32 v143, v93
	v_exp_f32_e32 v239, v94
	v_exp_f32_e32 v241, v95
	v_add_f32_e32 v221, v132, v221
	s_waitcnt lgkmcnt(8)
	v_mfma_f32_32x32x16_bf16 v[32:47], v[84:87], v[80:83], v[32:47]
	v_add_f32_e32 v93, v225, v223
	v_add_f32_e32 v221, v134, v221
	v_add_f32_e32 v93, v227, v93
	v_add_f32_e32 v221, v136, v221
	v_add_f32_e32 v93, v229, v93
	v_add_f32_e32 v221, v138, v221
	s_waitcnt lgkmcnt(10)
	v_mfma_f32_32x32x16_bf16 v[16:31], v[128:131], v[80:83], v[16:31]
	v_add_f32_e32 v93, v231, v93
	v_add_f32_e32 v221, v140, v221
	v_add_f32_e32 v93, v233, v93
	v_add_f32_e32 v221, v142, v221
	v_add_f32_e32 v93, v235, v93
	v_add_f32_e32 v221, v238, v221
	v_add_f32_e32 v93, v237, v93
	s_waitcnt lgkmcnt(0)
	v_mfma_f32_32x32x16_bf16 v[0:15], v[88:91], v[80:83], v[0:15]
	v_cvt_pk_bf16_f32 v80, v133, v135
	v_cvt_pk_bf16_f32 v81, v137, v139
	v_cvt_pk_bf16_f32 v82, v141, v143
	v_cvt_pk_bf16_f32 v83, v239, v241
	v_add_f32_e32 v221, v240, v221
	v_add_f32_e32 v93, v133, v93
	s_waitcnt lgkmcnt(12)
	v_mfma_f32_32x32x16_bf16 v[48:63], v[108:111], v[80:83], v[48:63]
	v_add_f32_e32 v93, v135, v93
	v_add_f32_e32 v93, v137, v93
	s_waitcnt lgkmcnt(6)
	v_mfma_f32_32x32x16_bf16 v[32:47], v[242:245], v[80:83], v[32:47]
	v_add_f32_e32 v93, v139, v93
	v_add_f32_e32 v93, v141, v93
	s_waitcnt lgkmcnt(4)
	v_mfma_f32_32x32x16_bf16 v[16:31], v[246:249], v[80:83], v[16:31]
	v_add_f32_e32 v93, v143, v93
	v_add_f32_e32 v93, v239, v93
	s_waitcnt lgkmcnt(2)
	v_mfma_f32_32x32x16_bf16 v[0:15], v[250:253], v[80:83], v[0:15]
	v_add_f32_e32 v93, v241, v93
	v_add_f32_e32 v221, v221, v93
	v_add_f32_e32 v146, v146, v221

; #define LOADV(dst, ks_) do { _Pragma("unroll") for (int dvb = 0; dvb < 4; ++dvb) { dst[2 * dvb] = vtr(vp + dvb * 4096 + (ks_) * 1024); dst[2 * dvb + 1] = vtr(vp + dvb * 4096 + (ks_) * 1024 + 512); } } while (0)
; #define MF4(src, pfrag) do { _Pragma("unroll") for (int dvb = 0; dvb < 4; ++dvb) { \
;         const bf16x8 vf_ = __builtin_shufflevector(src[2 * dvb], src[2 * dvb + 1], 0, 1, 2, 3, 4, 5, 6, 7); o[dvb] = MFMA32(vf_, pfrag, o[dvb]); } } while (0)
; #define EXPQ(S, lo_, RS, PF) do { _Pragma("unroll") for (int i = lo_; i < lo_ + 8; ++i) { S[i] = ex2(S[i]); RS += S[i]; } \
;               u32x4 w_; w_.x = pk2(S[lo_], S[lo_ + 1]); w_.y = pk2(S[lo_ + 2], S[lo_ + 3]); w_.z = pk2(S[lo_ + 4], S[lo_ + 5]); w_.w = pk2(S[lo_ + 6], S[lo_ + 7]); PF = __builtin_bit_cast(bf16x8, w_); } while (0)
; DI void attn_unit(const Params& p, int bh, int qb, char* lds, float lam, int tid, int lane, int wid, const bool build_tab) {
;     ...
;             float rs0 = 0.f, rs1 = 0.f;
;     ...
;             EXPQ(s0, 0, rs0, pf[0]);
;             LOADV(vb, 1);
;             MF4(va, pf[0]);
;             EXPQ(s0, 8, rs1, pf[1]);
;             LOADV(va, 2);
;             MF4(vb, pf[1]);
;             EXPQ(s1, 0, rs0, pf[2]);
;             LOADV(vb, 3);
;             MF4(va, pf[2]);
;             EXPQ(s1, 8, rs1, pf[3]);
;             MF4(vb, pf[3]);
;             l += rs0 + rs1;
.LBB0_379:
	ds_read_b64_tr_b16 v[230:231], v177 offset:21504
	ds_read_b64_tr_b16 v[232:233], v177 offset:22016
	ds_read_b64_tr_b16 v[234:235], v177 offset:25600
	ds_read_b64_tr_b16 v[236:237], v177 offset:26112
	v_exp_f32_e32 v178, v96
	v_exp_f32_e32 v180, v97
	v_exp_f32_e32 v182, v98
	v_exp_f32_e32 v184, v99
	v_exp_f32_e32 v186, v100
	v_exp_f32_e32 v188, v101
	v_exp_f32_e32 v190, v102
	v_exp_f32_e32 v192, v103
	v_cvt_pk_bf16_f32 v96, v178, v180
	v_cvt_pk_bf16_f32 v97, v182, v184
	v_cvt_pk_bf16_f32 v98, v186, v188
	v_cvt_pk_bf16_f32 v99, v190, v192
	ds_read_b64_tr_b16 v[100:101], v177 offset:17408
	ds_read_b64_tr_b16 v[102:103], v177 offset:17920
	s_waitcnt lgkmcnt(12)
	v_mfma_f32_32x32x16_bf16 v[48:63], v[140:143], v[96:99], v[48:63]
	ds_read_b64_tr_b16 v[238:239], v177 offset:29696
	ds_read_b64_tr_b16 v[240:241], v177 offset:30208
	v_exp_f32_e32 v179, v104
	v_exp_f32_e32 v181, v105
	v_exp_f32_e32 v183, v106
	v_add_f32_e32 v242, v180, v178
	s_waitcnt lgkmcnt(12)
	v_mfma_f32_32x32x16_bf16 v[32:47], v[136:139], v[96:99], v[32:47]
	v_exp_f32_e32 v185, v107
	v_exp_f32_e32 v187, v108
	v_exp_f32_e32 v189, v109
	v_add_f32_e32 v242, v182, v242
	s_waitcnt lgkmcnt(10)
	v_mfma_f32_32x32x16_bf16 v[16:31], v[132:135], v[96:99], v[16:31]
	v_exp_f32_e32 v191, v110
	v_exp_f32_e32 v193, v111
	v_add_f32_e32 v242, v184, v242
	v_add_f32_e32 v242, v186, v242
	ds_read_b64_tr_b16 v[104:105], v177 offset:18432
	ds_read_b64_tr_b16 v[106:107], v177 offset:18944
	ds_read_b64_tr_b16 v[108:109], v177 offset:19456
	ds_read_b64_tr_b16 v[110:111], v177 offset:19968
	s_waitcnt lgkmcnt(12)
	v_mfma_f32_32x32x16_bf16 v[0:15], v[128:131], v[96:99], v[0:15]
	s_setprio 0
	ds_read_b64_tr_b16 v[128:129], v177 offset:26624
	ds_read_b64_tr_b16 v[130:131], v177 offset:27136
	v_cvt_pk_bf16_f32 v96, v179, v181
	v_cvt_pk_bf16_f32 v97, v183, v185
	v_cvt_pk_bf16_f32 v98, v187, v189
	v_cvt_pk_bf16_f32 v99, v191, v193
	v_exp_f32_e32 v140, v84
	v_exp_f32_e32 v142, v85
	s_waitcnt lgkmcnt(8)
	v_mfma_f32_32x32x16_bf16 v[48:63], v[100:103], v[96:99], v[48:63]
	v_exp_f32_e32 v194, v86
	v_exp_f32_e32 v196, v87
	v_add_f32_e32 v242, v188, v242
	ds_read_b64_tr_b16 v[84:85], v177 offset:22528
	ds_read_b64_tr_b16 v[86:87], v177 offset:23040
	v_exp_f32_e32 v136, v82
	s_waitcnt lgkmcnt(14)
	v_mfma_f32_32x32x16_bf16 v[32:47], v[230:233], v[96:99], v[32:47]
	ds_read_b64_tr_b16 v[230:231], v177 offset:23552
	ds_read_b64_tr_b16 v[232:233], v177 offset:24064
	v_exp_f32_e32 v138, v83
	v_exp_f32_e32 v132, v80
	v_exp_f32_e32 v134, v81
	v_add_f32_e32 v242, v190, v242
	s_waitcnt lgkmcnt(14)
	v_mfma_f32_32x32x16_bf16 v[16:31], v[234:237], v[96:99], v[16:31]
	ds_read_b64_tr_b16 v[234:235], v177 offset:27648
	ds_read_b64_tr_b16 v[236:237], v177 offset:28160
	v_cvt_pk_bf16_f32 v80, v132, v134
	v_cvt_pk_bf16_f32 v81, v136, v138
	v_cvt_pk_bf16_f32 v82, v140, v142
	v_cvt_pk_bf16_f32 v83, v194, v196
	v_exp_f32_e32 v133, v88
	v_exp_f32_e32 v135, v89
	s_waitcnt lgkmcnt(12)
	v_mfma_f32_32x32x16_bf16 v[0:15], v[238:241], v[96:99], v[0:15]
	ds_read_b64_tr_b16 v[238:239], v177 offset:31744
	ds_read_b64_tr_b16 v[240:241], v177 offset:32256
	v_exp_f32_e32 v137, v90
	v_exp_f32_e32 v139, v91
	v_add_f32_e32 v242, v192, v242
	ds_read_b64_tr_b16 v[88:89], v177 offset:30720
	ds_read_b64_tr_b16 v[90:91], v177 offset:31232
	v_exp_f32_e32 v141, v92
	s_waitcnt lgkmcnt(14)
	v_mfma_f32_32x32x16_bf16 v[48:63], v[104:107], v[80:83], v[48:63]
	v_exp_f32_e32 v143, v93
	v_exp_f32_e32 v195, v94
	v_exp_f32_e32 v197, v95
	v_add_f32_e32 v242, v132, v242
	s_waitcnt lgkmcnt(8)
	v_mfma_f32_32x32x16_bf16 v[32:47], v[84:87], v[80:83], v[32:47]
	v_add_f32_e32 v243, v181, v179
	v_add_f32_e32 v242, v134, v242
	v_add_f32_e32 v243, v183, v243
	v_add_f32_e32 v242, v136, v242
	v_add_f32_e32 v243, v185, v243
	v_add_f32_e32 v242, v138, v242
	s_waitcnt lgkmcnt(10)
	v_mfma_f32_32x32x16_bf16 v[16:31], v[128:131], v[80:83], v[16:31]
	v_add_f32_e32 v243, v187, v243
	v_add_f32_e32 v242, v140, v242
	v_add_f32_e32 v243, v189, v243
	v_add_f32_e32 v242, v142, v242
	v_add_f32_e32 v243, v191, v243
	v_add_f32_e32 v242, v194, v242
	v_add_f32_e32 v243, v193, v243
	s_waitcnt lgkmcnt(0)
	v_mfma_f32_32x32x16_bf16 v[0:15], v[88:91], v[80:83], v[0:15]
	v_cvt_pk_bf16_f32 v80, v133, v135
	v_cvt_pk_bf16_f32 v81, v137, v139
	v_cvt_pk_bf16_f32 v82, v141, v143
	v_cvt_pk_bf16_f32 v83, v195, v197
	v_add_f32_e32 v242, v196, v242
	v_add_f32_e32 v243, v133, v243
	s_waitcnt lgkmcnt(12)
	v_mfma_f32_32x32x16_bf16 v[48:63], v[108:111], v[80:83], v[48:63]
	v_add_f32_e32 v243, v135, v243
	v_add_f32_e32 v243, v137, v243
	s_waitcnt lgkmcnt(6)
	v_mfma_f32_32x32x16_bf16 v[32:47], v[230:233], v[80:83], v[32:47]
	v_add_f32_e32 v243, v139, v243
	v_add_f32_e32 v243, v141, v243
	s_waitcnt lgkmcnt(4)
	v_mfma_f32_32x32x16_bf16 v[16:31], v[234:237], v[80:83], v[16:31]
	v_add_f32_e32 v243, v143, v243
	v_add_f32_e32 v243, v195, v243
	s_waitcnt lgkmcnt(2)
	v_mfma_f32_32x32x16_bf16 v[0:15], v[238:241], v[80:83], v[0:15]
	v_add_f32_e32 v243, v197, v243
	v_add_f32_e32 v242, v242, v243
	v_add_f32_e32 v176, v176, v242
